# combined variant with shortened GQA s_nop and a four-buffer (three rows ahead) P7 norm loop
# speedup vs baseline: 1.0124x; 1.0052x over previous
; __device__ __forceinline__ unsigned cvt_pk_bf16(float lo, float hi) { unsigned r; asm volatile("v_cvt_pk_bf16_f32 %0, %1, %2" : "=v"(r) : "v"(lo), "v"(hi)); return r; }
; __device__ __forceinline__ void norm_row_mod(const float* xrow, const float* sh, const float* sc, bf16_t* orow, int lane) {
;     const f32x4* xr = (const f32x4*)xrow + lane;
;     f32x4 v[4]; float s = 0.f;
; #pragma unroll
;     for (int j = 0; j < 4; ++j) { v[j] = xr[64 * j]; s += (v[j].x * v[j].x + v[j].y * v[j].y) + (v[j].z * v[j].z + v[j].w * v[j].w); }
;     const float rstd = rsqrtf(wave_sum(s, lane) * (1.f / DM) + EPS);
;     u32x2* o8 = (u32x2*)orow + lane;
; #pragma unroll
;     for (int j = 0; j < 4; ++j) { const f32x4 a = ((const f32x4*)sh)[lane + 64 * j], b = ((const f32x4*)sc)[lane + 64 * j];
;         const f32x4 y = v[j] * rstd * (b + 1.0f) + a;
;         u32x2 w; w.x = cvt_pk_bf16(y.x, y.y); w.y = cvt_pk_bf16(y.z, y.w); o8[64 * j] = w; }
; __global__ void __launch_bounds__(512, 2) mega_fwd(Args a) {
;     ...
;         { PHASE_IDS();
;         for (int rep = 0; rep < PROBE_AUX; ++rep)
;         for (int m = gw; m < Mrows; m += NGW) {
;             const bool isl = m < TL; const int j = isl ? (m >> 12) : 8;
;             const float* xr = isl ? OUTP + (size_t)m * DM : CX + (size_t)(m - TL) * DM;
;             norm_row_mod(xr, modl + (size_t)j * NMOD + 3 * DM, modl + (size_t)j * NMOD + 4 * DM, XN + (size_t)m * DM, lane);
;         }
.LBB0_747:
	s_or_b64 exec, exec, s[0:1]
	v_readlane_b32 s0, v254, 7
	s_add_i32 s8, s0, s70
	v_readlane_b32 s0, v252, 3
	v_readlane_b32 s1, v252, 4
	s_cmp_ge_i32 s8, s24
	s_waitcnt lgkmcnt(0)
	s_barrier
	v_mbcnt_lo_u32_b32 v0, -1, 0
	v_mbcnt_hi_u32_b32 v0, -1, v0
	s_cbranch_scc1 .LBB0_754
	s_load_dwordx2 s[4:5], s[0:1], 0xc8
	v_ashrrev_i32_e32 v1, 31, v0
	v_lshlrev_b32_e32 v2, 2, v0
	v_xor_b32_e32 v23, 4, v2
	v_xor_b32_e32 v28, 8, v2
	s_waitcnt lgkmcnt(0)
	s_add_u32 s16, s4, 0x1900000
	s_addc_u32 s17, s5, 0
	s_lshl_b64 s[6:7], s[66:67], 2
	s_add_u32 s18, s4, s6
	s_addc_u32 s19, s5, s7
	v_xor_b32_e32 v29, 16, v2
	v_xor_b32_e32 v30, 32, v2
	v_xor_b32_e32 v31, 64, v2
	v_xor_b32_e32 v32, 0x80, v2
	v_lshl_add_u64 v[2:3], v[0:1], 3, s[4:5]
	s_mov_b64 s[4:5], 0x3c00000
	s_ashr_i32 s9, s8, 31
	v_lshl_add_u64 v[16:17], v[2:3], 0, s[4:5]
	s_lshl_b64 s[4:5], s[8:9], 12
	v_lshlrev_b64 v[18:19], 4, v[0:1]
	s_mov_b64 s[6:7], s[8:9]
	s_load_dwordx2 s[10:11], s[0:1], 0xc0
	s_waitcnt lgkmcnt(0)
	s_cmpk_gt_i32 s6, 0x7fff
	s_cselect_b32 s12, s16, s10
	s_cselect_b32 s13, s17, s11
	s_cselect_b32 s14, 0x8000, 0
	s_sub_i32 s14, s6, s14
	s_mov_b32 s15, 0
	s_lshl_b64 s[14:15], s[14:15], 12
	s_add_u32 s14, s14, s12
	s_addc_u32 s15, s15, s13
	v_lshl_add_u64 v[2:3], s[14:15], 0, v[18:19]
	global_load_dwordx4 v[64:67], v[2:3], off
	global_load_dwordx4 v[68:71], v[2:3], off offset:1024
	global_load_dwordx4 v[72:75], v[2:3], off offset:2048
	global_load_dwordx4 v[76:79], v[2:3], off offset:3072
	s_mov_b32 s9, s6
	s_add_i32 s9, s9, s62
	s_cmp_lt_i32 s9, s24
	s_cselect_b32 s9, s9, s6
	s_cmpk_gt_i32 s9, 0x7fff
	s_cselect_b32 s12, s16, s10
	s_cselect_b32 s13, s17, s11
	s_cselect_b32 s14, 0x8000, 0
	s_sub_i32 s14, s9, s14
	s_mov_b32 s15, 0
	s_lshl_b64 s[14:15], s[14:15], 12
	s_add_u32 s14, s14, s12
	s_addc_u32 s15, s15, s13
	v_lshl_add_u64 v[2:3], s[14:15], 0, v[18:19]
	global_load_dwordx4 v[80:83], v[2:3], off
	global_load_dwordx4 v[84:87], v[2:3], off offset:1024
	global_load_dwordx4 v[88:91], v[2:3], off offset:2048
	global_load_dwordx4 v[92:95], v[2:3], off offset:3072
	s_mov_b32 s9, s6
	s_add_i32 s9, s9, s62
	s_add_i32 s9, s9, s62
	s_cmp_lt_i32 s9, s24
	s_cselect_b32 s9, s9, s6
	s_cmpk_gt_i32 s9, 0x7fff
	s_cselect_b32 s12, s16, s10
	s_cselect_b32 s13, s17, s11
	s_cselect_b32 s14, 0x8000, 0
	s_sub_i32 s14, s9, s14
	s_mov_b32 s15, 0
	s_lshl_b64 s[14:15], s[14:15], 12
	s_add_u32 s14, s14, s12
	s_addc_u32 s15, s15, s13
	v_lshl_add_u64 v[2:3], s[14:15], 0, v[18:19]
	global_load_dwordx4 v[96:99], v[2:3], off
	global_load_dwordx4 v[100:103], v[2:3], off offset:1024
	global_load_dwordx4 v[104:107], v[2:3], off offset:2048
	global_load_dwordx4 v[108:111], v[2:3], off offset:3072
	s_min_i32 s9, s6, 0x8000
	s_ashr_i32 s9, s9, 12
	s_mul_i32 s9, s9, 0x6000
	s_add_u32 s12, s18, s9
	s_addc_u32 s13, s19, 0
	s_add_u32 s12, s12, 0x4000
	s_addc_u32 s13, s13, 0
	v_lshl_add_u64 v[0:1], s[12:13], 0, v[18:19]
	global_load_dwordx4 v[164:167], v[0:1], off offset:-4096
	global_load_dwordx4 v[168:171], v[0:1], off offset:-3072
	global_load_dwordx4 v[172:175], v[0:1], off offset:-2048
	global_load_dwordx4 v[176:179], v[0:1], off offset:-1024
	global_load_dwordx4 v[180:183], v[0:1], off
	global_load_dwordx4 v[184:187], v[0:1], off offset:1024
	global_load_dwordx4 v[188:191], v[0:1], off offset:2048
	global_load_dwordx4 v[192:195], v[0:1], off offset:3072
	s_mov_b32 s9, s6
	s_add_i32 s9, s9, s62
	s_add_i32 s9, s9, s62
	s_add_i32 s9, s9, s62
	s_cmp_lt_i32 s9, s24
	s_cselect_b32 s9, s9, s6
	s_cmpk_gt_i32 s9, 0x7fff
	s_cselect_b32 s12, s16, s10
	s_cselect_b32 s13, s17, s11
	s_cselect_b32 s14, 0x8000, 0
	s_sub_i32 s14, s9, s14
	s_mov_b32 s15, 0
	s_lshl_b64 s[14:15], s[14:15], 12
	s_add_u32 s14, s14, s12
	s_addc_u32 s15, s15, s13
	v_lshl_add_u64 v[2:3], s[14:15], 0, v[18:19]
	global_load_dwordx4 v[206:209], v[2:3], off
	global_load_dwordx4 v[210:213], v[2:3], off offset:1024
	global_load_dwordx4 v[214:217], v[2:3], off offset:2048
	global_load_dwordx4 v[218:221], v[2:3], off offset:3072
	s_mov_b32 s12, s6
	s_mov_b32 s13, 0
	s_lshl_b64 s[12:13], s[12:13], 11
	v_lshl_add_u64 v[4:5], v[16:17], 0, s[12:13]
	s_waitcnt vmcnt(20)
	v_pk_mul_f32 v[20:21], v[64:65], v[64:65]
	v_pk_fma_f32 v[20:21], v[66:67], v[66:67], v[20:21]
	v_pk_fma_f32 v[20:21], v[68:69], v[68:69], v[20:21]
	v_pk_fma_f32 v[20:21], v[70:71], v[70:71], v[20:21]
	v_pk_fma_f32 v[20:21], v[72:73], v[72:73], v[20:21]
	v_pk_fma_f32 v[20:21], v[74:75], v[74:75], v[20:21]
	v_pk_fma_f32 v[20:21], v[76:77], v[76:77], v[20:21]
	v_pk_fma_f32 v[20:21], v[78:79], v[78:79], v[20:21]
	s_nop 0
	v_add_f32_e32 v20, v20, v21
	ds_bpermute_b32 v24, v23, v20
	s_waitcnt lgkmcnt(0)
	v_add_f32_e32 v20, v20, v24
	ds_bpermute_b32 v24, v28, v20
	s_waitcnt lgkmcnt(0)
	v_add_f32_e32 v20, v20, v24
	ds_bpermute_b32 v24, v29, v20
	s_waitcnt lgkmcnt(0)
	v_add_f32_e32 v20, v20, v24
	ds_bpermute_b32 v24, v30, v20
	s_waitcnt lgkmcnt(0)
	v_add_f32_e32 v20, v20, v24
	ds_bpermute_b32 v24, v31, v20
	s_waitcnt lgkmcnt(0)
	v_add_f32_e32 v20, v20, v24
	ds_bpermute_b32 v24, v32, v20
	s_waitcnt lgkmcnt(0)
	v_add_f32_e32 v20, v20, v24
	v_fmamk_f32 v20, v20, 0x3a800000, v205
	v_mul_f32_e32 v24, 0x4b800000, v20
	v_cmp_gt_f32_e32 vcc, s2, v20
	s_nop 1
	v_cndmask_b32_e32 v20, v20, v24, vcc
	v_rsq_f32_e32 v20, v20
	s_nop 0
	v_mul_f32_e32 v24, 0x45800000, v20
	v_cndmask_b32_e32 v22, v20, v24, vcc
	s_waitcnt vmcnt(4)
; __device__ __forceinline__ unsigned cvt_pk_bf16(float lo, float hi) { unsigned r; asm volatile("v_cvt_pk_bf16_f32 %0, %1, %2" : "=v"(r) : "v"(lo), "v"(hi)); return r; }
; __device__ __forceinline__ void norm_row_mod(const float* xrow, const float* sh, const float* sc, bf16_t* orow, int lane) {
;     const f32x4* xr = (const f32x4*)xrow + lane;
;     f32x4 v[4]; float s = 0.f;
; #pragma unroll
;     for (int j = 0; j < 4; ++j) { v[j] = xr[64 * j]; s += (v[j].x * v[j].x + v[j].y * v[j].y) + (v[j].z * v[j].z + v[j].w * v[j].w); }
;     const float rstd = rsqrtf(wave_sum(s, lane) * (1.f / DM) + EPS);
;     u32x2* o8 = (u32x2*)orow + lane;
; #pragma unroll
;     for (int j = 0; j < 4; ++j) { const f32x4 a = ((const f32x4*)sh)[lane + 64 * j], b = ((const f32x4*)sc)[lane + 64 * j];
;         const f32x4 y = v[j] * rstd * (b + 1.0f) + a;
;         u32x2 w; w.x = cvt_pk_bf16(y.x, y.y); w.y = cvt_pk_bf16(y.z, y.w); o8[64 * j] = w; }
; __global__ void __launch_bounds__(512, 2) mega_fwd(Args a) {
;     ...
;         for (int m = gw; m < Mrows; m += NGW) {
;             const bool isl = m < TL; const int j = isl ? (m >> 12) : 8;
;             const float* xr = isl ? OUTP + (size_t)m * DM : CX + (size_t)(m - TL) * DM;
;             norm_row_mod(xr, modl + (size_t)j * NMOD + 3 * DM, modl + (size_t)j * NMOD + 4 * DM, XN + (size_t)m * DM, lane);
	v_pk_mul_f32 v[64:65], v[64:65], v[22:23] op_sel_hi:[1,0]
	v_pk_mul_f32 v[66:67], v[66:67], v[22:23] op_sel_hi:[1,0]
	v_pk_add_f32 v[180:181], v[180:181], 1.0 op_sel_hi:[1,0]
	v_pk_add_f32 v[182:183], v[182:183], 1.0 op_sel_hi:[1,0]
	v_pk_fma_f32 v[64:65], v[180:181], v[64:65], v[164:165]
	v_pk_fma_f32 v[66:67], v[182:183], v[66:67], v[166:167]
	v_cvt_pk_bf16_f32 v64, v64, v65
	v_cvt_pk_bf16_f32 v65, v66, v67
	global_store_dwordx2 v[4:5], v[64:65], off
	v_pk_mul_f32 v[68:69], v[68:69], v[22:23] op_sel_hi:[1,0]
	v_pk_mul_f32 v[70:71], v[70:71], v[22:23] op_sel_hi:[1,0]
	v_pk_add_f32 v[184:185], v[184:185], 1.0 op_sel_hi:[1,0]
	v_pk_add_f32 v[186:187], v[186:187], 1.0 op_sel_hi:[1,0]
	v_pk_fma_f32 v[68:69], v[184:185], v[68:69], v[168:169]
	v_pk_fma_f32 v[70:71], v[186:187], v[70:71], v[170:171]
	v_cvt_pk_bf16_f32 v68, v68, v69
	v_cvt_pk_bf16_f32 v69, v70, v71
	global_store_dwordx2 v[4:5], v[68:69], off offset:512
	v_pk_mul_f32 v[72:73], v[72:73], v[22:23] op_sel_hi:[1,0]
	v_pk_mul_f32 v[74:75], v[74:75], v[22:23] op_sel_hi:[1,0]
	v_pk_add_f32 v[188:189], v[188:189], 1.0 op_sel_hi:[1,0]
	v_pk_add_f32 v[190:191], v[190:191], 1.0 op_sel_hi:[1,0]
	v_pk_fma_f32 v[72:73], v[188:189], v[72:73], v[172:173]
	v_pk_fma_f32 v[74:75], v[190:191], v[74:75], v[174:175]
	v_cvt_pk_bf16_f32 v72, v72, v73
	v_cvt_pk_bf16_f32 v73, v74, v75
	global_store_dwordx2 v[4:5], v[72:73], off offset:1024
	v_pk_mul_f32 v[76:77], v[76:77], v[22:23] op_sel_hi:[1,0]
	v_pk_mul_f32 v[78:79], v[78:79], v[22:23] op_sel_hi:[1,0]
	v_pk_add_f32 v[192:193], v[192:193], 1.0 op_sel_hi:[1,0]
	v_pk_add_f32 v[194:195], v[194:195], 1.0 op_sel_hi:[1,0]
	v_pk_fma_f32 v[76:77], v[192:193], v[76:77], v[176:177]
	v_pk_fma_f32 v[78:79], v[194:195], v[78:79], v[178:179]
	v_cvt_pk_bf16_f32 v76, v76, v77
	v_cvt_pk_bf16_f32 v77, v78, v79
	global_store_dwordx2 v[4:5], v[76:77], off offset:1536
	s_add_i32 s6, s6, s62
	s_cmp_ge_i32 s6, s24
	s_cbranch_scc1 .Lp7_done
	s_min_i32 s9, s6, 0x8000
	s_ashr_i32 s9, s9, 12
	s_mul_i32 s9, s9, 0x6000
	s_add_u32 s12, s18, s9
	s_addc_u32 s13, s19, 0
	s_add_u32 s12, s12, 0x4000
	s_addc_u32 s13, s13, 0
	v_lshl_add_u64 v[0:1], s[12:13], 0, v[18:19]
	global_load_dwordx4 v[164:167], v[0:1], off offset:-4096
	global_load_dwordx4 v[168:171], v[0:1], off offset:-3072
	global_load_dwordx4 v[172:175], v[0:1], off offset:-2048
	global_load_dwordx4 v[176:179], v[0:1], off offset:-1024
	global_load_dwordx4 v[180:183], v[0:1], off
	global_load_dwordx4 v[184:187], v[0:1], off offset:1024
	global_load_dwordx4 v[188:191], v[0:1], off offset:2048
	global_load_dwordx4 v[192:195], v[0:1], off offset:3072
	s_mov_b32 s9, s6
	s_add_i32 s9, s9, s62
	s_add_i32 s9, s9, s62
	s_add_i32 s9, s9, s62
	s_cmp_lt_i32 s9, s24
	s_cselect_b32 s9, s9, s6
	s_cmpk_gt_i32 s9, 0x7fff
	s_cselect_b32 s12, s16, s10
	s_cselect_b32 s13, s17, s11
	s_cselect_b32 s14, 0x8000, 0
	s_sub_i32 s14, s9, s14
	s_mov_b32 s15, 0
	s_lshl_b64 s[14:15], s[14:15], 12
	s_add_u32 s14, s14, s12
	s_addc_u32 s15, s15, s13
	v_lshl_add_u64 v[2:3], s[14:15], 0, v[18:19]
	global_load_dwordx4 v[64:67], v[2:3], off
	global_load_dwordx4 v[68:71], v[2:3], off offset:1024
	global_load_dwordx4 v[72:75], v[2:3], off offset:2048
	global_load_dwordx4 v[76:79], v[2:3], off offset:3072
	s_mov_b32 s12, s6
	s_mov_b32 s13, 0
	s_lshl_b64 s[12:13], s[12:13], 11
	v_lshl_add_u64 v[4:5], v[16:17], 0, s[12:13]
	s_waitcnt vmcnt(32)
	v_pk_mul_f32 v[20:21], v[80:81], v[80:81]
	v_pk_fma_f32 v[20:21], v[82:83], v[82:83], v[20:21]
	v_pk_fma_f32 v[20:21], v[84:85], v[84:85], v[20:21]
	v_pk_fma_f32 v[20:21], v[86:87], v[86:87], v[20:21]
	v_pk_fma_f32 v[20:21], v[88:89], v[88:89], v[20:21]
	v_pk_fma_f32 v[20:21], v[90:91], v[90:91], v[20:21]
	v_pk_fma_f32 v[20:21], v[92:93], v[92:93], v[20:21]
	v_pk_fma_f32 v[20:21], v[94:95], v[94:95], v[20:21]
	s_nop 0
	v_add_f32_e32 v20, v20, v21
	ds_bpermute_b32 v24, v23, v20
	s_waitcnt lgkmcnt(0)
	v_add_f32_e32 v20, v20, v24
	ds_bpermute_b32 v24, v28, v20
	s_waitcnt lgkmcnt(0)
	v_add_f32_e32 v20, v20, v24
	ds_bpermute_b32 v24, v29, v20
	s_waitcnt lgkmcnt(0)
	v_add_f32_e32 v20, v20, v24
	ds_bpermute_b32 v24, v30, v20
	s_waitcnt lgkmcnt(0)
	v_add_f32_e32 v20, v20, v24
	ds_bpermute_b32 v24, v31, v20
	s_waitcnt lgkmcnt(0)
	v_add_f32_e32 v20, v20, v24
	ds_bpermute_b32 v24, v32, v20
	s_waitcnt lgkmcnt(0)
	v_add_f32_e32 v20, v20, v24
	v_fmamk_f32 v20, v20, 0x3a800000, v205
	v_mul_f32_e32 v24, 0x4b800000, v20
	v_cmp_gt_f32_e32 vcc, s2, v20
	s_nop 1
	v_cndmask_b32_e32 v20, v20, v24, vcc
	v_rsq_f32_e32 v20, v20
	s_nop 0
	v_mul_f32_e32 v24, 0x45800000, v20
	v_cndmask_b32_e32 v22, v20, v24, vcc
	s_waitcnt vmcnt(4)
	v_pk_mul_f32 v[80:81], v[80:81], v[22:23] op_sel_hi:[1,0]
	v_pk_mul_f32 v[82:83], v[82:83], v[22:23] op_sel_hi:[1,0]
	v_pk_add_f32 v[180:181], v[180:181], 1.0 op_sel_hi:[1,0]
	v_pk_add_f32 v[182:183], v[182:183], 1.0 op_sel_hi:[1,0]
	v_pk_fma_f32 v[80:81], v[180:181], v[80:81], v[164:165]
	v_pk_fma_f32 v[82:83], v[182:183], v[82:83], v[166:167]
	v_cvt_pk_bf16_f32 v80, v80, v81
	v_cvt_pk_bf16_f32 v81, v82, v83
	global_store_dwordx2 v[4:5], v[80:81], off
	v_pk_mul_f32 v[84:85], v[84:85], v[22:23] op_sel_hi:[1,0]
	v_pk_mul_f32 v[86:87], v[86:87], v[22:23] op_sel_hi:[1,0]
	v_pk_add_f32 v[184:185], v[184:185], 1.0 op_sel_hi:[1,0]
	v_pk_add_f32 v[186:187], v[186:187], 1.0 op_sel_hi:[1,0]
	v_pk_fma_f32 v[84:85], v[184:185], v[84:85], v[168:169]
	v_pk_fma_f32 v[86:87], v[186:187], v[86:87], v[170:171]
	v_cvt_pk_bf16_f32 v84, v84, v85
	v_cvt_pk_bf16_f32 v85, v86, v87
	global_store_dwordx2 v[4:5], v[84:85], off offset:512
	v_pk_mul_f32 v[88:89], v[88:89], v[22:23] op_sel_hi:[1,0]
	v_pk_mul_f32 v[90:91], v[90:91], v[22:23] op_sel_hi:[1,0]
	v_pk_add_f32 v[188:189], v[188:189], 1.0 op_sel_hi:[1,0]
	v_pk_add_f32 v[190:191], v[190:191], 1.0 op_sel_hi:[1,0]
	v_pk_fma_f32 v[88:89], v[188:189], v[88:89], v[172:173]
	v_pk_fma_f32 v[90:91], v[190:191], v[90:91], v[174:175]
	v_cvt_pk_bf16_f32 v88, v88, v89
	v_cvt_pk_bf16_f32 v89, v90, v91
	global_store_dwordx2 v[4:5], v[88:89], off offset:1024
	v_pk_mul_f32 v[92:93], v[92:93], v[22:23] op_sel_hi:[1,0]
	v_pk_mul_f32 v[94:95], v[94:95], v[22:23] op_sel_hi:[1,0]
	v_pk_add_f32 v[192:193], v[192:193], 1.0 op_sel_hi:[1,0]
	v_pk_add_f32 v[194:195], v[194:195], 1.0 op_sel_hi:[1,0]
	v_pk_fma_f32 v[92:93], v[192:193], v[92:93], v[176:177]
	v_pk_fma_f32 v[94:95], v[194:195], v[94:95], v[178:179]
	v_cvt_pk_bf16_f32 v92, v92, v93
	v_cvt_pk_bf16_f32 v93, v94, v95
	global_store_dwordx2 v[4:5], v[92:93], off offset:1536
	s_add_i32 s6, s6, s62
	s_cmp_ge_i32 s6, s24
	s_cbranch_scc1 .Lp7_done
; __device__ __forceinline__ unsigned cvt_pk_bf16(float lo, float hi) { unsigned r; asm volatile("v_cvt_pk_bf16_f32 %0, %1, %2" : "=v"(r) : "v"(lo), "v"(hi)); return r; }
; __device__ __forceinline__ void norm_row_mod(const float* xrow, const float* sh, const float* sc, bf16_t* orow, int lane) {
;     const f32x4* xr = (const f32x4*)xrow + lane;
;     f32x4 v[4]; float s = 0.f;
; #pragma unroll
;     for (int j = 0; j < 4; ++j) { v[j] = xr[64 * j]; s += (v[j].x * v[j].x + v[j].y * v[j].y) + (v[j].z * v[j].z + v[j].w * v[j].w); }
;     const float rstd = rsqrtf(wave_sum(s, lane) * (1.f / DM) + EPS);
;     u32x2* o8 = (u32x2*)orow + lane;
; #pragma unroll
;     for (int j = 0; j < 4; ++j) { const f32x4 a = ((const f32x4*)sh)[lane + 64 * j], b = ((const f32x4*)sc)[lane + 64 * j];
;         const f32x4 y = v[j] * rstd * (b + 1.0f) + a;
;         u32x2 w; w.x = cvt_pk_bf16(y.x, y.y); w.y = cvt_pk_bf16(y.z, y.w); o8[64 * j] = w; }
; __global__ void __launch_bounds__(512, 2) mega_fwd(Args a) {
;     ...
;         for (int m = gw; m < Mrows; m += NGW) {
;             const bool isl = m < TL; const int j = isl ? (m >> 12) : 8;
;             const float* xr = isl ? OUTP + (size_t)m * DM : CX + (size_t)(m - TL) * DM;
;             norm_row_mod(xr, modl + (size_t)j * NMOD + 3 * DM, modl + (size_t)j * NMOD + 4 * DM, XN + (size_t)m * DM, lane);
	s_min_i32 s9, s6, 0x8000
	s_ashr_i32 s9, s9, 12
	s_mul_i32 s9, s9, 0x6000
	s_add_u32 s12, s18, s9
	s_addc_u32 s13, s19, 0
	s_add_u32 s12, s12, 0x4000
	s_addc_u32 s13, s13, 0
	v_lshl_add_u64 v[0:1], s[12:13], 0, v[18:19]
	global_load_dwordx4 v[164:167], v[0:1], off offset:-4096
	global_load_dwordx4 v[168:171], v[0:1], off offset:-3072
	global_load_dwordx4 v[172:175], v[0:1], off offset:-2048
	global_load_dwordx4 v[176:179], v[0:1], off offset:-1024
	global_load_dwordx4 v[180:183], v[0:1], off
	global_load_dwordx4 v[184:187], v[0:1], off offset:1024
	global_load_dwordx4 v[188:191], v[0:1], off offset:2048
	global_load_dwordx4 v[192:195], v[0:1], off offset:3072
	s_mov_b32 s9, s6
	s_add_i32 s9, s9, s62
	s_add_i32 s9, s9, s62
	s_add_i32 s9, s9, s62
	s_cmp_lt_i32 s9, s24
	s_cselect_b32 s9, s9, s6
	s_cmpk_gt_i32 s9, 0x7fff
	s_cselect_b32 s12, s16, s10
	s_cselect_b32 s13, s17, s11
	s_cselect_b32 s14, 0x8000, 0
	s_sub_i32 s14, s9, s14
	s_mov_b32 s15, 0
	s_lshl_b64 s[14:15], s[14:15], 12
	s_add_u32 s14, s14, s12
	s_addc_u32 s15, s15, s13
	v_lshl_add_u64 v[2:3], s[14:15], 0, v[18:19]
	global_load_dwordx4 v[80:83], v[2:3], off
	global_load_dwordx4 v[84:87], v[2:3], off offset:1024
	global_load_dwordx4 v[88:91], v[2:3], off offset:2048
	global_load_dwordx4 v[92:95], v[2:3], off offset:3072
	s_mov_b32 s12, s6
	s_mov_b32 s13, 0
	s_lshl_b64 s[12:13], s[12:13], 11
	v_lshl_add_u64 v[4:5], v[16:17], 0, s[12:13]
	s_waitcnt vmcnt(44)
	v_pk_mul_f32 v[20:21], v[96:97], v[96:97]
	v_pk_fma_f32 v[20:21], v[98:99], v[98:99], v[20:21]
	v_pk_fma_f32 v[20:21], v[100:101], v[100:101], v[20:21]
	v_pk_fma_f32 v[20:21], v[102:103], v[102:103], v[20:21]
	v_pk_fma_f32 v[20:21], v[104:105], v[104:105], v[20:21]
	v_pk_fma_f32 v[20:21], v[106:107], v[106:107], v[20:21]
	v_pk_fma_f32 v[20:21], v[108:109], v[108:109], v[20:21]
	v_pk_fma_f32 v[20:21], v[110:111], v[110:111], v[20:21]
	s_nop 0
	v_add_f32_e32 v20, v20, v21
	ds_bpermute_b32 v24, v23, v20
	s_waitcnt lgkmcnt(0)
	v_add_f32_e32 v20, v20, v24
	ds_bpermute_b32 v24, v28, v20
	s_waitcnt lgkmcnt(0)
	v_add_f32_e32 v20, v20, v24
	ds_bpermute_b32 v24, v29, v20
	s_waitcnt lgkmcnt(0)
	v_add_f32_e32 v20, v20, v24
	ds_bpermute_b32 v24, v30, v20
	s_waitcnt lgkmcnt(0)
	v_add_f32_e32 v20, v20, v24
	ds_bpermute_b32 v24, v31, v20
	s_waitcnt lgkmcnt(0)
	v_add_f32_e32 v20, v20, v24
	ds_bpermute_b32 v24, v32, v20
	s_waitcnt lgkmcnt(0)
	v_add_f32_e32 v20, v20, v24
	v_fmamk_f32 v20, v20, 0x3a800000, v205
	v_mul_f32_e32 v24, 0x4b800000, v20
	v_cmp_gt_f32_e32 vcc, s2, v20
	s_nop 1
	v_cndmask_b32_e32 v20, v20, v24, vcc
	v_rsq_f32_e32 v20, v20
	s_nop 0
	v_mul_f32_e32 v24, 0x45800000, v20
	v_cndmask_b32_e32 v22, v20, v24, vcc
	s_waitcnt vmcnt(4)
	v_pk_mul_f32 v[96:97], v[96:97], v[22:23] op_sel_hi:[1,0]
	v_pk_mul_f32 v[98:99], v[98:99], v[22:23] op_sel_hi:[1,0]
	v_pk_add_f32 v[180:181], v[180:181], 1.0 op_sel_hi:[1,0]
	v_pk_add_f32 v[182:183], v[182:183], 1.0 op_sel_hi:[1,0]
	v_pk_fma_f32 v[96:97], v[180:181], v[96:97], v[164:165]
	v_pk_fma_f32 v[98:99], v[182:183], v[98:99], v[166:167]
	v_cvt_pk_bf16_f32 v96, v96, v97
	v_cvt_pk_bf16_f32 v97, v98, v99
	global_store_dwordx2 v[4:5], v[96:97], off
	v_pk_mul_f32 v[100:101], v[100:101], v[22:23] op_sel_hi:[1,0]
	v_pk_mul_f32 v[102:103], v[102:103], v[22:23] op_sel_hi:[1,0]
	v_pk_add_f32 v[184:185], v[184:185], 1.0 op_sel_hi:[1,0]
	v_pk_add_f32 v[186:187], v[186:187], 1.0 op_sel_hi:[1,0]
	v_pk_fma_f32 v[100:101], v[184:185], v[100:101], v[168:169]
	v_pk_fma_f32 v[102:103], v[186:187], v[102:103], v[170:171]
	v_cvt_pk_bf16_f32 v100, v100, v101
	v_cvt_pk_bf16_f32 v101, v102, v103
	global_store_dwordx2 v[4:5], v[100:101], off offset:512
	v_pk_mul_f32 v[104:105], v[104:105], v[22:23] op_sel_hi:[1,0]
	v_pk_mul_f32 v[106:107], v[106:107], v[22:23] op_sel_hi:[1,0]
	v_pk_add_f32 v[188:189], v[188:189], 1.0 op_sel_hi:[1,0]
	v_pk_add_f32 v[190:191], v[190:191], 1.0 op_sel_hi:[1,0]
	v_pk_fma_f32 v[104:105], v[188:189], v[104:105], v[172:173]
	v_pk_fma_f32 v[106:107], v[190:191], v[106:107], v[174:175]
	v_cvt_pk_bf16_f32 v104, v104, v105
	v_cvt_pk_bf16_f32 v105, v106, v107
	global_store_dwordx2 v[4:5], v[104:105], off offset:1024
	v_pk_mul_f32 v[108:109], v[108:109], v[22:23] op_sel_hi:[1,0]
	v_pk_mul_f32 v[110:111], v[110:111], v[22:23] op_sel_hi:[1,0]
	v_pk_add_f32 v[192:193], v[192:193], 1.0 op_sel_hi:[1,0]
	v_pk_add_f32 v[194:195], v[194:195], 1.0 op_sel_hi:[1,0]
	v_pk_fma_f32 v[108:109], v[192:193], v[108:109], v[176:177]
	v_pk_fma_f32 v[110:111], v[194:195], v[110:111], v[178:179]
	v_cvt_pk_bf16_f32 v108, v108, v109
	v_cvt_pk_bf16_f32 v109, v110, v111
	global_store_dwordx2 v[4:5], v[108:109], off offset:1536
	s_add_i32 s6, s6, s62
	s_cmp_ge_i32 s6, s24
	s_cbranch_scc1 .Lp7_done
; __device__ __forceinline__ unsigned cvt_pk_bf16(float lo, float hi) { unsigned r; asm volatile("v_cvt_pk_bf16_f32 %0, %1, %2" : "=v"(r) : "v"(lo), "v"(hi)); return r; }
; __device__ __forceinline__ void norm_row_mod(const float* xrow, const float* sh, const float* sc, bf16_t* orow, int lane) {
;     const f32x4* xr = (const f32x4*)xrow + lane;
;     f32x4 v[4]; float s = 0.f;
; #pragma unroll
;     for (int j = 0; j < 4; ++j) { v[j] = xr[64 * j]; s += (v[j].x * v[j].x + v[j].y * v[j].y) + (v[j].z * v[j].z + v[j].w * v[j].w); }
;     const float rstd = rsqrtf(wave_sum(s, lane) * (1.f / DM) + EPS);
;     u32x2* o8 = (u32x2*)orow + lane;
; #pragma unroll
;     for (int j = 0; j < 4; ++j) { const f32x4 a = ((const f32x4*)sh)[lane + 64 * j], b = ((const f32x4*)sc)[lane + 64 * j];
;         const f32x4 y = v[j] * rstd * (b + 1.0f) + a;
;         u32x2 w; w.x = cvt_pk_bf16(y.x, y.y); w.y = cvt_pk_bf16(y.z, y.w); o8[64 * j] = w; }
; __global__ void __launch_bounds__(512, 2) mega_fwd(Args a) {
;     ...
;         for (int m = gw; m < Mrows; m += NGW) {
;             const bool isl = m < TL; const int j = isl ? (m >> 12) : 8;
;             const float* xr = isl ? OUTP + (size_t)m * DM : CX + (size_t)(m - TL) * DM;
;             norm_row_mod(xr, modl + (size_t)j * NMOD + 3 * DM, modl + (size_t)j * NMOD + 4 * DM, XN + (size_t)m * DM, lane);
.Lp7_loop:
	s_min_i32 s9, s6, 0x8000
	s_ashr_i32 s9, s9, 12
	s_mul_i32 s9, s9, 0x6000
	s_add_u32 s12, s18, s9
	s_addc_u32 s13, s19, 0
	s_add_u32 s12, s12, 0x4000
	s_addc_u32 s13, s13, 0
	v_lshl_add_u64 v[0:1], s[12:13], 0, v[18:19]
	global_load_dwordx4 v[164:167], v[0:1], off offset:-4096
	global_load_dwordx4 v[168:171], v[0:1], off offset:-3072
	global_load_dwordx4 v[172:175], v[0:1], off offset:-2048
	global_load_dwordx4 v[176:179], v[0:1], off offset:-1024
	global_load_dwordx4 v[180:183], v[0:1], off
	global_load_dwordx4 v[184:187], v[0:1], off offset:1024
	global_load_dwordx4 v[188:191], v[0:1], off offset:2048
	global_load_dwordx4 v[192:195], v[0:1], off offset:3072
	s_mov_b32 s9, s6
	s_add_i32 s9, s9, s62
	s_add_i32 s9, s9, s62
	s_add_i32 s9, s9, s62
	s_cmp_lt_i32 s9, s24
	s_cselect_b32 s9, s9, s6
	s_cmpk_gt_i32 s9, 0x7fff
	s_cselect_b32 s12, s16, s10
	s_cselect_b32 s13, s17, s11
	s_cselect_b32 s14, 0x8000, 0
	s_sub_i32 s14, s9, s14
	s_mov_b32 s15, 0
	s_lshl_b64 s[14:15], s[14:15], 12
	s_add_u32 s14, s14, s12
	s_addc_u32 s15, s15, s13
	v_lshl_add_u64 v[2:3], s[14:15], 0, v[18:19]
	global_load_dwordx4 v[96:99], v[2:3], off
	global_load_dwordx4 v[100:103], v[2:3], off offset:1024
	global_load_dwordx4 v[104:107], v[2:3], off offset:2048
	global_load_dwordx4 v[108:111], v[2:3], off offset:3072
	s_mov_b32 s12, s6
	s_mov_b32 s13, 0
	s_lshl_b64 s[12:13], s[12:13], 11
	v_lshl_add_u64 v[4:5], v[16:17], 0, s[12:13]
	s_waitcnt vmcnt(48)
	v_pk_mul_f32 v[20:21], v[206:207], v[206:207]
	v_pk_fma_f32 v[20:21], v[208:209], v[208:209], v[20:21]
	v_pk_fma_f32 v[20:21], v[210:211], v[210:211], v[20:21]
	v_pk_fma_f32 v[20:21], v[212:213], v[212:213], v[20:21]
	v_pk_fma_f32 v[20:21], v[214:215], v[214:215], v[20:21]
	v_pk_fma_f32 v[20:21], v[216:217], v[216:217], v[20:21]
	v_pk_fma_f32 v[20:21], v[218:219], v[218:219], v[20:21]
	v_pk_fma_f32 v[20:21], v[220:221], v[220:221], v[20:21]
	s_nop 0
	v_add_f32_e32 v20, v20, v21
	ds_bpermute_b32 v24, v23, v20
	s_waitcnt lgkmcnt(0)
	v_add_f32_e32 v20, v20, v24
	ds_bpermute_b32 v24, v28, v20
	s_waitcnt lgkmcnt(0)
	v_add_f32_e32 v20, v20, v24
	ds_bpermute_b32 v24, v29, v20
	s_waitcnt lgkmcnt(0)
	v_add_f32_e32 v20, v20, v24
	ds_bpermute_b32 v24, v30, v20
	s_waitcnt lgkmcnt(0)
	v_add_f32_e32 v20, v20, v24
	ds_bpermute_b32 v24, v31, v20
	s_waitcnt lgkmcnt(0)
	v_add_f32_e32 v20, v20, v24
	ds_bpermute_b32 v24, v32, v20
	s_waitcnt lgkmcnt(0)
	v_add_f32_e32 v20, v20, v24
	v_fmamk_f32 v20, v20, 0x3a800000, v205
	v_mul_f32_e32 v24, 0x4b800000, v20
	v_cmp_gt_f32_e32 vcc, s2, v20
	s_nop 1
	v_cndmask_b32_e32 v20, v20, v24, vcc
	v_rsq_f32_e32 v20, v20
	s_nop 0
	v_mul_f32_e32 v24, 0x45800000, v20
	v_cndmask_b32_e32 v22, v20, v24, vcc
	s_waitcnt vmcnt(4)
	v_pk_mul_f32 v[206:207], v[206:207], v[22:23] op_sel_hi:[1,0]
	v_pk_mul_f32 v[208:209], v[208:209], v[22:23] op_sel_hi:[1,0]
	v_pk_add_f32 v[180:181], v[180:181], 1.0 op_sel_hi:[1,0]
	v_pk_add_f32 v[182:183], v[182:183], 1.0 op_sel_hi:[1,0]
	v_pk_fma_f32 v[206:207], v[180:181], v[206:207], v[164:165]
	v_pk_fma_f32 v[208:209], v[182:183], v[208:209], v[166:167]
	v_cvt_pk_bf16_f32 v206, v206, v207
	v_cvt_pk_bf16_f32 v207, v208, v209
	global_store_dwordx2 v[4:5], v[206:207], off
	v_pk_mul_f32 v[210:211], v[210:211], v[22:23] op_sel_hi:[1,0]
	v_pk_mul_f32 v[212:213], v[212:213], v[22:23] op_sel_hi:[1,0]
	v_pk_add_f32 v[184:185], v[184:185], 1.0 op_sel_hi:[1,0]
	v_pk_add_f32 v[186:187], v[186:187], 1.0 op_sel_hi:[1,0]
	v_pk_fma_f32 v[210:211], v[184:185], v[210:211], v[168:169]
	v_pk_fma_f32 v[212:213], v[186:187], v[212:213], v[170:171]
	v_cvt_pk_bf16_f32 v210, v210, v211
	v_cvt_pk_bf16_f32 v211, v212, v213
	global_store_dwordx2 v[4:5], v[210:211], off offset:512
	v_pk_mul_f32 v[214:215], v[214:215], v[22:23] op_sel_hi:[1,0]
	v_pk_mul_f32 v[216:217], v[216:217], v[22:23] op_sel_hi:[1,0]
	v_pk_add_f32 v[188:189], v[188:189], 1.0 op_sel_hi:[1,0]
	v_pk_add_f32 v[190:191], v[190:191], 1.0 op_sel_hi:[1,0]
	v_pk_fma_f32 v[214:215], v[188:189], v[214:215], v[172:173]
	v_pk_fma_f32 v[216:217], v[190:191], v[216:217], v[174:175]
	v_cvt_pk_bf16_f32 v214, v214, v215
	v_cvt_pk_bf16_f32 v215, v216, v217
	global_store_dwordx2 v[4:5], v[214:215], off offset:1024
	v_pk_mul_f32 v[218:219], v[218:219], v[22:23] op_sel_hi:[1,0]
	v_pk_mul_f32 v[220:221], v[220:221], v[22:23] op_sel_hi:[1,0]
	v_pk_add_f32 v[192:193], v[192:193], 1.0 op_sel_hi:[1,0]
	v_pk_add_f32 v[194:195], v[194:195], 1.0 op_sel_hi:[1,0]
	v_pk_fma_f32 v[218:219], v[192:193], v[218:219], v[176:177]
	v_pk_fma_f32 v[220:221], v[194:195], v[220:221], v[178:179]
	v_cvt_pk_bf16_f32 v218, v218, v219
	v_cvt_pk_bf16_f32 v219, v220, v221
	global_store_dwordx2 v[4:5], v[218:219], off offset:1536
	s_add_i32 s6, s6, s62
	s_cmp_ge_i32 s6, s24
	s_cbranch_scc1 .Lp7_done
; __device__ __forceinline__ unsigned cvt_pk_bf16(float lo, float hi) { unsigned r; asm volatile("v_cvt_pk_bf16_f32 %0, %1, %2" : "=v"(r) : "v"(lo), "v"(hi)); return r; }
; __device__ __forceinline__ void norm_row_mod(const float* xrow, const float* sh, const float* sc, bf16_t* orow, int lane) {
;     const f32x4* xr = (const f32x4*)xrow + lane;
;     f32x4 v[4]; float s = 0.f;
; #pragma unroll
;     for (int j = 0; j < 4; ++j) { v[j] = xr[64 * j]; s += (v[j].x * v[j].x + v[j].y * v[j].y) + (v[j].z * v[j].z + v[j].w * v[j].w); }
;     const float rstd = rsqrtf(wave_sum(s, lane) * (1.f / DM) + EPS);
;     u32x2* o8 = (u32x2*)orow + lane;
; #pragma unroll
;     for (int j = 0; j < 4; ++j) { const f32x4 a = ((const f32x4*)sh)[lane + 64 * j], b = ((const f32x4*)sc)[lane + 64 * j];
;         const f32x4 y = v[j] * rstd * (b + 1.0f) + a;
;         u32x2 w; w.x = cvt_pk_bf16(y.x, y.y); w.y = cvt_pk_bf16(y.z, y.w); o8[64 * j] = w; }
; __global__ void __launch_bounds__(512, 2) mega_fwd(Args a) {
;     ...
;         for (int m = gw; m < Mrows; m += NGW) {
;             const bool isl = m < TL; const int j = isl ? (m >> 12) : 8;
;             const float* xr = isl ? OUTP + (size_t)m * DM : CX + (size_t)(m - TL) * DM;
;             norm_row_mod(xr, modl + (size_t)j * NMOD + 3 * DM, modl + (size_t)j * NMOD + 4 * DM, XN + (size_t)m * DM, lane);
	s_min_i32 s9, s6, 0x8000
	s_ashr_i32 s9, s9, 12
	s_mul_i32 s9, s9, 0x6000
	s_add_u32 s12, s18, s9
	s_addc_u32 s13, s19, 0
	s_add_u32 s12, s12, 0x4000
	s_addc_u32 s13, s13, 0
	v_lshl_add_u64 v[0:1], s[12:13], 0, v[18:19]
	global_load_dwordx4 v[164:167], v[0:1], off offset:-4096
	global_load_dwordx4 v[168:171], v[0:1], off offset:-3072
	global_load_dwordx4 v[172:175], v[0:1], off offset:-2048
	global_load_dwordx4 v[176:179], v[0:1], off offset:-1024
	global_load_dwordx4 v[180:183], v[0:1], off
	global_load_dwordx4 v[184:187], v[0:1], off offset:1024
	global_load_dwordx4 v[188:191], v[0:1], off offset:2048
	global_load_dwordx4 v[192:195], v[0:1], off offset:3072
	s_mov_b32 s9, s6
	s_add_i32 s9, s9, s62
	s_add_i32 s9, s9, s62
	s_add_i32 s9, s9, s62
	s_cmp_lt_i32 s9, s24
	s_cselect_b32 s9, s9, s6
	s_cmpk_gt_i32 s9, 0x7fff
	s_cselect_b32 s12, s16, s10
	s_cselect_b32 s13, s17, s11
	s_cselect_b32 s14, 0x8000, 0
	s_sub_i32 s14, s9, s14
	s_mov_b32 s15, 0
	s_lshl_b64 s[14:15], s[14:15], 12
	s_add_u32 s14, s14, s12
	s_addc_u32 s15, s15, s13
	v_lshl_add_u64 v[2:3], s[14:15], 0, v[18:19]
	global_load_dwordx4 v[206:209], v[2:3], off
	global_load_dwordx4 v[210:213], v[2:3], off offset:1024
	global_load_dwordx4 v[214:217], v[2:3], off offset:2048
	global_load_dwordx4 v[218:221], v[2:3], off offset:3072
	s_mov_b32 s12, s6
	s_mov_b32 s13, 0
	s_lshl_b64 s[12:13], s[12:13], 11
	v_lshl_add_u64 v[4:5], v[16:17], 0, s[12:13]
	s_waitcnt vmcnt(48)
	v_pk_mul_f32 v[20:21], v[64:65], v[64:65]
	v_pk_fma_f32 v[20:21], v[66:67], v[66:67], v[20:21]
	v_pk_fma_f32 v[20:21], v[68:69], v[68:69], v[20:21]
	v_pk_fma_f32 v[20:21], v[70:71], v[70:71], v[20:21]
	v_pk_fma_f32 v[20:21], v[72:73], v[72:73], v[20:21]
	v_pk_fma_f32 v[20:21], v[74:75], v[74:75], v[20:21]
	v_pk_fma_f32 v[20:21], v[76:77], v[76:77], v[20:21]
	v_pk_fma_f32 v[20:21], v[78:79], v[78:79], v[20:21]
	s_nop 0
	v_add_f32_e32 v20, v20, v21
	ds_bpermute_b32 v24, v23, v20
	s_waitcnt lgkmcnt(0)
	v_add_f32_e32 v20, v20, v24
	ds_bpermute_b32 v24, v28, v20
	s_waitcnt lgkmcnt(0)
	v_add_f32_e32 v20, v20, v24
	ds_bpermute_b32 v24, v29, v20
	s_waitcnt lgkmcnt(0)
	v_add_f32_e32 v20, v20, v24
	ds_bpermute_b32 v24, v30, v20
	s_waitcnt lgkmcnt(0)
	v_add_f32_e32 v20, v20, v24
	ds_bpermute_b32 v24, v31, v20
	s_waitcnt lgkmcnt(0)
	v_add_f32_e32 v20, v20, v24
	ds_bpermute_b32 v24, v32, v20
	s_waitcnt lgkmcnt(0)
	v_add_f32_e32 v20, v20, v24
	v_fmamk_f32 v20, v20, 0x3a800000, v205
	v_mul_f32_e32 v24, 0x4b800000, v20
	v_cmp_gt_f32_e32 vcc, s2, v20
	s_nop 1
	v_cndmask_b32_e32 v20, v20, v24, vcc
	v_rsq_f32_e32 v20, v20
	s_nop 0
	v_mul_f32_e32 v24, 0x45800000, v20
	v_cndmask_b32_e32 v22, v20, v24, vcc
	s_waitcnt vmcnt(4)
	v_pk_mul_f32 v[64:65], v[64:65], v[22:23] op_sel_hi:[1,0]
	v_pk_mul_f32 v[66:67], v[66:67], v[22:23] op_sel_hi:[1,0]
	v_pk_add_f32 v[180:181], v[180:181], 1.0 op_sel_hi:[1,0]
	v_pk_add_f32 v[182:183], v[182:183], 1.0 op_sel_hi:[1,0]
	v_pk_fma_f32 v[64:65], v[180:181], v[64:65], v[164:165]
	v_pk_fma_f32 v[66:67], v[182:183], v[66:67], v[166:167]
	v_cvt_pk_bf16_f32 v64, v64, v65
	v_cvt_pk_bf16_f32 v65, v66, v67
	global_store_dwordx2 v[4:5], v[64:65], off
	v_pk_mul_f32 v[68:69], v[68:69], v[22:23] op_sel_hi:[1,0]
	v_pk_mul_f32 v[70:71], v[70:71], v[22:23] op_sel_hi:[1,0]
	v_pk_add_f32 v[184:185], v[184:185], 1.0 op_sel_hi:[1,0]
	v_pk_add_f32 v[186:187], v[186:187], 1.0 op_sel_hi:[1,0]
	v_pk_fma_f32 v[68:69], v[184:185], v[68:69], v[168:169]
	v_pk_fma_f32 v[70:71], v[186:187], v[70:71], v[170:171]
	v_cvt_pk_bf16_f32 v68, v68, v69
	v_cvt_pk_bf16_f32 v69, v70, v71
	global_store_dwordx2 v[4:5], v[68:69], off offset:512
	v_pk_mul_f32 v[72:73], v[72:73], v[22:23] op_sel_hi:[1,0]
	v_pk_mul_f32 v[74:75], v[74:75], v[22:23] op_sel_hi:[1,0]
	v_pk_add_f32 v[188:189], v[188:189], 1.0 op_sel_hi:[1,0]
	v_pk_add_f32 v[190:191], v[190:191], 1.0 op_sel_hi:[1,0]
	v_pk_fma_f32 v[72:73], v[188:189], v[72:73], v[172:173]
	v_pk_fma_f32 v[74:75], v[190:191], v[74:75], v[174:175]
	v_cvt_pk_bf16_f32 v72, v72, v73
	v_cvt_pk_bf16_f32 v73, v74, v75
	global_store_dwordx2 v[4:5], v[72:73], off offset:1024
	v_pk_mul_f32 v[76:77], v[76:77], v[22:23] op_sel_hi:[1,0]
	v_pk_mul_f32 v[78:79], v[78:79], v[22:23] op_sel_hi:[1,0]
	v_pk_add_f32 v[192:193], v[192:193], 1.0 op_sel_hi:[1,0]
	v_pk_add_f32 v[194:195], v[194:195], 1.0 op_sel_hi:[1,0]
	v_pk_fma_f32 v[76:77], v[192:193], v[76:77], v[176:177]
	v_pk_fma_f32 v[78:79], v[194:195], v[78:79], v[178:179]
	v_cvt_pk_bf16_f32 v76, v76, v77
	v_cvt_pk_bf16_f32 v77, v78, v79
	global_store_dwordx2 v[4:5], v[76:77], off offset:1536
	s_add_i32 s6, s6, s62
	s_cmp_ge_i32 s6, s24
	s_cbranch_scc1 .Lp7_done
; __device__ __forceinline__ unsigned cvt_pk_bf16(float lo, float hi) { unsigned r; asm volatile("v_cvt_pk_bf16_f32 %0, %1, %2" : "=v"(r) : "v"(lo), "v"(hi)); return r; }
; __device__ __forceinline__ void norm_row_mod(const float* xrow, const float* sh, const float* sc, bf16_t* orow, int lane) {
;     const f32x4* xr = (const f32x4*)xrow + lane;
;     f32x4 v[4]; float s = 0.f;
; #pragma unroll
;     for (int j = 0; j < 4; ++j) { v[j] = xr[64 * j]; s += (v[j].x * v[j].x + v[j].y * v[j].y) + (v[j].z * v[j].z + v[j].w * v[j].w); }
;     const float rstd = rsqrtf(wave_sum(s, lane) * (1.f / DM) + EPS);
;     u32x2* o8 = (u32x2*)orow + lane;
; #pragma unroll
;     for (int j = 0; j < 4; ++j) { const f32x4 a = ((const f32x4*)sh)[lane + 64 * j], b = ((const f32x4*)sc)[lane + 64 * j];
;         const f32x4 y = v[j] * rstd * (b + 1.0f) + a;
;         u32x2 w; w.x = cvt_pk_bf16(y.x, y.y); w.y = cvt_pk_bf16(y.z, y.w); o8[64 * j] = w; }
; __global__ void __launch_bounds__(512, 2) mega_fwd(Args a) {
;     ...
;         for (int m = gw; m < Mrows; m += NGW) {
;             const bool isl = m < TL; const int j = isl ? (m >> 12) : 8;
;             const float* xr = isl ? OUTP + (size_t)m * DM : CX + (size_t)(m - TL) * DM;
;             norm_row_mod(xr, modl + (size_t)j * NMOD + 3 * DM, modl + (size_t)j * NMOD + 4 * DM, XN + (size_t)m * DM, lane);
	s_min_i32 s9, s6, 0x8000
	s_ashr_i32 s9, s9, 12
	s_mul_i32 s9, s9, 0x6000
	s_add_u32 s12, s18, s9
	s_addc_u32 s13, s19, 0
	s_add_u32 s12, s12, 0x4000
	s_addc_u32 s13, s13, 0
	v_lshl_add_u64 v[0:1], s[12:13], 0, v[18:19]
	global_load_dwordx4 v[164:167], v[0:1], off offset:-4096
	global_load_dwordx4 v[168:171], v[0:1], off offset:-3072
	global_load_dwordx4 v[172:175], v[0:1], off offset:-2048
	global_load_dwordx4 v[176:179], v[0:1], off offset:-1024
	global_load_dwordx4 v[180:183], v[0:1], off
	global_load_dwordx4 v[184:187], v[0:1], off offset:1024
	global_load_dwordx4 v[188:191], v[0:1], off offset:2048
	global_load_dwordx4 v[192:195], v[0:1], off offset:3072
	s_mov_b32 s9, s6
	s_add_i32 s9, s9, s62
	s_add_i32 s9, s9, s62
	s_add_i32 s9, s9, s62
	s_cmp_lt_i32 s9, s24
	s_cselect_b32 s9, s9, s6
	s_cmpk_gt_i32 s9, 0x7fff
	s_cselect_b32 s12, s16, s10
	s_cselect_b32 s13, s17, s11
	s_cselect_b32 s14, 0x8000, 0
	s_sub_i32 s14, s9, s14
	s_mov_b32 s15, 0
	s_lshl_b64 s[14:15], s[14:15], 12
	s_add_u32 s14, s14, s12
	s_addc_u32 s15, s15, s13
	v_lshl_add_u64 v[2:3], s[14:15], 0, v[18:19]
	global_load_dwordx4 v[64:67], v[2:3], off
	global_load_dwordx4 v[68:71], v[2:3], off offset:1024
	global_load_dwordx4 v[72:75], v[2:3], off offset:2048
	global_load_dwordx4 v[76:79], v[2:3], off offset:3072
	s_mov_b32 s12, s6
	s_mov_b32 s13, 0
	s_lshl_b64 s[12:13], s[12:13], 11
	v_lshl_add_u64 v[4:5], v[16:17], 0, s[12:13]
	s_waitcnt vmcnt(48)
	v_pk_mul_f32 v[20:21], v[80:81], v[80:81]
	v_pk_fma_f32 v[20:21], v[82:83], v[82:83], v[20:21]
	v_pk_fma_f32 v[20:21], v[84:85], v[84:85], v[20:21]
	v_pk_fma_f32 v[20:21], v[86:87], v[86:87], v[20:21]
	v_pk_fma_f32 v[20:21], v[88:89], v[88:89], v[20:21]
	v_pk_fma_f32 v[20:21], v[90:91], v[90:91], v[20:21]
	v_pk_fma_f32 v[20:21], v[92:93], v[92:93], v[20:21]
	v_pk_fma_f32 v[20:21], v[94:95], v[94:95], v[20:21]
	s_nop 0
	v_add_f32_e32 v20, v20, v21
	ds_bpermute_b32 v24, v23, v20
	s_waitcnt lgkmcnt(0)
	v_add_f32_e32 v20, v20, v24
	ds_bpermute_b32 v24, v28, v20
	s_waitcnt lgkmcnt(0)
	v_add_f32_e32 v20, v20, v24
	ds_bpermute_b32 v24, v29, v20
	s_waitcnt lgkmcnt(0)
	v_add_f32_e32 v20, v20, v24
	ds_bpermute_b32 v24, v30, v20
	s_waitcnt lgkmcnt(0)
	v_add_f32_e32 v20, v20, v24
	ds_bpermute_b32 v24, v31, v20
	s_waitcnt lgkmcnt(0)
	v_add_f32_e32 v20, v20, v24
	ds_bpermute_b32 v24, v32, v20
	s_waitcnt lgkmcnt(0)
	v_add_f32_e32 v20, v20, v24
	v_fmamk_f32 v20, v20, 0x3a800000, v205
	v_mul_f32_e32 v24, 0x4b800000, v20
	v_cmp_gt_f32_e32 vcc, s2, v20
	s_nop 1
	v_cndmask_b32_e32 v20, v20, v24, vcc
	v_rsq_f32_e32 v20, v20
	s_nop 0
	v_mul_f32_e32 v24, 0x45800000, v20
	v_cndmask_b32_e32 v22, v20, v24, vcc
	s_waitcnt vmcnt(4)
	v_pk_mul_f32 v[80:81], v[80:81], v[22:23] op_sel_hi:[1,0]
	v_pk_mul_f32 v[82:83], v[82:83], v[22:23] op_sel_hi:[1,0]
	v_pk_add_f32 v[180:181], v[180:181], 1.0 op_sel_hi:[1,0]
	v_pk_add_f32 v[182:183], v[182:183], 1.0 op_sel_hi:[1,0]
	v_pk_fma_f32 v[80:81], v[180:181], v[80:81], v[164:165]
	v_pk_fma_f32 v[82:83], v[182:183], v[82:83], v[166:167]
	v_cvt_pk_bf16_f32 v80, v80, v81
	v_cvt_pk_bf16_f32 v81, v82, v83
	global_store_dwordx2 v[4:5], v[80:81], off
	v_pk_mul_f32 v[84:85], v[84:85], v[22:23] op_sel_hi:[1,0]
	v_pk_mul_f32 v[86:87], v[86:87], v[22:23] op_sel_hi:[1,0]
	v_pk_add_f32 v[184:185], v[184:185], 1.0 op_sel_hi:[1,0]
	v_pk_add_f32 v[186:187], v[186:187], 1.0 op_sel_hi:[1,0]
	v_pk_fma_f32 v[84:85], v[184:185], v[84:85], v[168:169]
	v_pk_fma_f32 v[86:87], v[186:187], v[86:87], v[170:171]
	v_cvt_pk_bf16_f32 v84, v84, v85
	v_cvt_pk_bf16_f32 v85, v86, v87
	global_store_dwordx2 v[4:5], v[84:85], off offset:512
	v_pk_mul_f32 v[88:89], v[88:89], v[22:23] op_sel_hi:[1,0]
	v_pk_mul_f32 v[90:91], v[90:91], v[22:23] op_sel_hi:[1,0]
	v_pk_add_f32 v[188:189], v[188:189], 1.0 op_sel_hi:[1,0]
	v_pk_add_f32 v[190:191], v[190:191], 1.0 op_sel_hi:[1,0]
	v_pk_fma_f32 v[88:89], v[188:189], v[88:89], v[172:173]
	v_pk_fma_f32 v[90:91], v[190:191], v[90:91], v[174:175]
	v_cvt_pk_bf16_f32 v88, v88, v89
	v_cvt_pk_bf16_f32 v89, v90, v91
	global_store_dwordx2 v[4:5], v[88:89], off offset:1024
	v_pk_mul_f32 v[92:93], v[92:93], v[22:23] op_sel_hi:[1,0]
	v_pk_mul_f32 v[94:95], v[94:95], v[22:23] op_sel_hi:[1,0]
	v_pk_add_f32 v[192:193], v[192:193], 1.0 op_sel_hi:[1,0]
	v_pk_add_f32 v[194:195], v[194:195], 1.0 op_sel_hi:[1,0]
	v_pk_fma_f32 v[92:93], v[192:193], v[92:93], v[176:177]
	v_pk_fma_f32 v[94:95], v[194:195], v[94:95], v[178:179]
	v_cvt_pk_bf16_f32 v92, v92, v93
	v_cvt_pk_bf16_f32 v93, v94, v95
	global_store_dwordx2 v[4:5], v[92:93], off offset:1536
	s_add_i32 s6, s6, s62
	s_cmp_ge_i32 s6, s24
	s_cbranch_scc1 .Lp7_done
; __device__ __forceinline__ unsigned cvt_pk_bf16(float lo, float hi) { unsigned r; asm volatile("v_cvt_pk_bf16_f32 %0, %1, %2" : "=v"(r) : "v"(lo), "v"(hi)); return r; }
; __device__ __forceinline__ void norm_row_mod(const float* xrow, const float* sh, const float* sc, bf16_t* orow, int lane) {
;     const f32x4* xr = (const f32x4*)xrow + lane;
;     f32x4 v[4]; float s = 0.f;
; #pragma unroll
;     for (int j = 0; j < 4; ++j) { v[j] = xr[64 * j]; s += (v[j].x * v[j].x + v[j].y * v[j].y) + (v[j].z * v[j].z + v[j].w * v[j].w); }
;     const float rstd = rsqrtf(wave_sum(s, lane) * (1.f / DM) + EPS);
;     u32x2* o8 = (u32x2*)orow + lane;
; #pragma unroll
;     for (int j = 0; j < 4; ++j) { const f32x4 a = ((const f32x4*)sh)[lane + 64 * j], b = ((const f32x4*)sc)[lane + 64 * j];
;         const f32x4 y = v[j] * rstd * (b + 1.0f) + a;
;         u32x2 w; w.x = cvt_pk_bf16(y.x, y.y); w.y = cvt_pk_bf16(y.z, y.w); o8[64 * j] = w; }
; __global__ void __launch_bounds__(512, 2) mega_fwd(Args a) {
;     ...
;         for (int m = gw; m < Mrows; m += NGW) {
;             const bool isl = m < TL; const int j = isl ? (m >> 12) : 8;
;             const float* xr = isl ? OUTP + (size_t)m * DM : CX + (size_t)(m - TL) * DM;
;             norm_row_mod(xr, modl + (size_t)j * NMOD + 3 * DM, modl + (size_t)j * NMOD + 4 * DM, XN + (size_t)m * DM, lane);
	s_min_i32 s9, s6, 0x8000
	s_ashr_i32 s9, s9, 12
	s_mul_i32 s9, s9, 0x6000
	s_add_u32 s12, s18, s9
	s_addc_u32 s13, s19, 0
	s_add_u32 s12, s12, 0x4000
	s_addc_u32 s13, s13, 0
	v_lshl_add_u64 v[0:1], s[12:13], 0, v[18:19]
	global_load_dwordx4 v[164:167], v[0:1], off offset:-4096
	global_load_dwordx4 v[168:171], v[0:1], off offset:-3072
	global_load_dwordx4 v[172:175], v[0:1], off offset:-2048
	global_load_dwordx4 v[176:179], v[0:1], off offset:-1024
	global_load_dwordx4 v[180:183], v[0:1], off
	global_load_dwordx4 v[184:187], v[0:1], off offset:1024
	global_load_dwordx4 v[188:191], v[0:1], off offset:2048
	global_load_dwordx4 v[192:195], v[0:1], off offset:3072
	s_mov_b32 s9, s6
	s_add_i32 s9, s9, s62
	s_add_i32 s9, s9, s62
	s_add_i32 s9, s9, s62
	s_cmp_lt_i32 s9, s24
	s_cselect_b32 s9, s9, s6
	s_cmpk_gt_i32 s9, 0x7fff
	s_cselect_b32 s12, s16, s10
	s_cselect_b32 s13, s17, s11
	s_cselect_b32 s14, 0x8000, 0
	s_sub_i32 s14, s9, s14
	s_mov_b32 s15, 0
	s_lshl_b64 s[14:15], s[14:15], 12
	s_add_u32 s14, s14, s12
	s_addc_u32 s15, s15, s13
	v_lshl_add_u64 v[2:3], s[14:15], 0, v[18:19]
	global_load_dwordx4 v[80:83], v[2:3], off
	global_load_dwordx4 v[84:87], v[2:3], off offset:1024
	global_load_dwordx4 v[88:91], v[2:3], off offset:2048
	global_load_dwordx4 v[92:95], v[2:3], off offset:3072
	s_mov_b32 s12, s6
	s_mov_b32 s13, 0
	s_lshl_b64 s[12:13], s[12:13], 11
	v_lshl_add_u64 v[4:5], v[16:17], 0, s[12:13]
	s_waitcnt vmcnt(48)
	v_pk_mul_f32 v[20:21], v[96:97], v[96:97]
	v_pk_fma_f32 v[20:21], v[98:99], v[98:99], v[20:21]
	v_pk_fma_f32 v[20:21], v[100:101], v[100:101], v[20:21]
	v_pk_fma_f32 v[20:21], v[102:103], v[102:103], v[20:21]
	v_pk_fma_f32 v[20:21], v[104:105], v[104:105], v[20:21]
	v_pk_fma_f32 v[20:21], v[106:107], v[106:107], v[20:21]
	v_pk_fma_f32 v[20:21], v[108:109], v[108:109], v[20:21]
	v_pk_fma_f32 v[20:21], v[110:111], v[110:111], v[20:21]
	s_nop 0
	v_add_f32_e32 v20, v20, v21
	ds_bpermute_b32 v24, v23, v20
	s_waitcnt lgkmcnt(0)
	v_add_f32_e32 v20, v20, v24
	ds_bpermute_b32 v24, v28, v20
	s_waitcnt lgkmcnt(0)
	v_add_f32_e32 v20, v20, v24
	ds_bpermute_b32 v24, v29, v20
	s_waitcnt lgkmcnt(0)
	v_add_f32_e32 v20, v20, v24
	ds_bpermute_b32 v24, v30, v20
	s_waitcnt lgkmcnt(0)
	v_add_f32_e32 v20, v20, v24
	ds_bpermute_b32 v24, v31, v20
	s_waitcnt lgkmcnt(0)
	v_add_f32_e32 v20, v20, v24
	ds_bpermute_b32 v24, v32, v20
	s_waitcnt lgkmcnt(0)
	v_add_f32_e32 v20, v20, v24
	v_fmamk_f32 v20, v20, 0x3a800000, v205
	v_mul_f32_e32 v24, 0x4b800000, v20
	v_cmp_gt_f32_e32 vcc, s2, v20
	s_nop 1
	v_cndmask_b32_e32 v20, v20, v24, vcc
	v_rsq_f32_e32 v20, v20
	s_nop 0
	v_mul_f32_e32 v24, 0x45800000, v20
	v_cndmask_b32_e32 v22, v20, v24, vcc
	s_waitcnt vmcnt(4)
	v_pk_mul_f32 v[96:97], v[96:97], v[22:23] op_sel_hi:[1,0]
	v_pk_mul_f32 v[98:99], v[98:99], v[22:23] op_sel_hi:[1,0]
	v_pk_add_f32 v[180:181], v[180:181], 1.0 op_sel_hi:[1,0]
	v_pk_add_f32 v[182:183], v[182:183], 1.0 op_sel_hi:[1,0]
	v_pk_fma_f32 v[96:97], v[180:181], v[96:97], v[164:165]
	v_pk_fma_f32 v[98:99], v[182:183], v[98:99], v[166:167]
	v_cvt_pk_bf16_f32 v96, v96, v97
	v_cvt_pk_bf16_f32 v97, v98, v99
	global_store_dwordx2 v[4:5], v[96:97], off
	v_pk_mul_f32 v[100:101], v[100:101], v[22:23] op_sel_hi:[1,0]
	v_pk_mul_f32 v[102:103], v[102:103], v[22:23] op_sel_hi:[1,0]
	v_pk_add_f32 v[184:185], v[184:185], 1.0 op_sel_hi:[1,0]
	v_pk_add_f32 v[186:187], v[186:187], 1.0 op_sel_hi:[1,0]
	v_pk_fma_f32 v[100:101], v[184:185], v[100:101], v[168:169]
	v_pk_fma_f32 v[102:103], v[186:187], v[102:103], v[170:171]
	v_cvt_pk_bf16_f32 v100, v100, v101
	v_cvt_pk_bf16_f32 v101, v102, v103
	global_store_dwordx2 v[4:5], v[100:101], off offset:512
	v_pk_mul_f32 v[104:105], v[104:105], v[22:23] op_sel_hi:[1,0]
	v_pk_mul_f32 v[106:107], v[106:107], v[22:23] op_sel_hi:[1,0]
	v_pk_add_f32 v[188:189], v[188:189], 1.0 op_sel_hi:[1,0]
	v_pk_add_f32 v[190:191], v[190:191], 1.0 op_sel_hi:[1,0]
	v_pk_fma_f32 v[104:105], v[188:189], v[104:105], v[172:173]
	v_pk_fma_f32 v[106:107], v[190:191], v[106:107], v[174:175]
	v_cvt_pk_bf16_f32 v104, v104, v105
	v_cvt_pk_bf16_f32 v105, v106, v107
	global_store_dwordx2 v[4:5], v[104:105], off offset:1024
	v_pk_mul_f32 v[108:109], v[108:109], v[22:23] op_sel_hi:[1,0]
	v_pk_mul_f32 v[110:111], v[110:111], v[22:23] op_sel_hi:[1,0]
	v_pk_add_f32 v[192:193], v[192:193], 1.0 op_sel_hi:[1,0]
	v_pk_add_f32 v[194:195], v[194:195], 1.0 op_sel_hi:[1,0]
	v_pk_fma_f32 v[108:109], v[192:193], v[108:109], v[176:177]
	v_pk_fma_f32 v[110:111], v[194:195], v[110:111], v[178:179]
	v_cvt_pk_bf16_f32 v108, v108, v109
	v_cvt_pk_bf16_f32 v109, v110, v111
	global_store_dwordx2 v[4:5], v[108:109], off offset:1536
	s_add_i32 s6, s6, s62
	s_cmp_ge_i32 s6, s24
	s_cbranch_scc1 .Lp7_done
	s_branch .Lp7_loop
